# P0 rmsnorm: gain vector loaded once; P9/P13 fused-norm epilogues: gain loads hoisted out of per-row-group code
# speedup vs baseline: 1.0533x; 1.0042x over previous
.LBB0_115:
	s_cmp_lt_i32 s78, 0x8000
	s_cselect_b64 s[16:17], -1, 0
	s_cmpk_gt_i32 s78, 0x7fff
	v_ashrrev_i32_e32 v195, 31, v194
	v_mbcnt_lo_u32_b32 v208, -1, 0
	s_cbranch_scc1 .LBB0_118
	v_mbcnt_hi_u32_b32 v2, -1, v208
	v_and_b32_e32 v3, 64, v2
	v_add_u32_e32 v3, 64, v3
	v_xor_b32_e32 v4, 1, v2
	v_cmp_lt_i32_e32 vcc, v4, v3
	s_mov_b64 s[4:5], 0x1400
	s_ashr_i32 s79, s78, 31
	v_cndmask_b32_e32 v4, v2, v4, vcc
	v_lshlrev_b32_e32 v20, 2, v4
	v_xor_b32_e32 v4, 2, v2
	v_cmp_lt_i32_e32 vcc, v4, v3
	s_mov_b64 s[2:3], 0x1000
	v_mov_b32_e32 v26, 0x358637bd
	v_cndmask_b32_e32 v4, v2, v4, vcc
	v_lshlrev_b32_e32 v21, 2, v4
	v_xor_b32_e32 v4, 4, v2
	v_cmp_lt_i32_e32 vcc, v4, v3
	s_nop 1
	v_cndmask_b32_e32 v4, v2, v4, vcc
	v_lshlrev_b32_e32 v22, 2, v4
	v_xor_b32_e32 v4, 8, v2
	v_cmp_lt_i32_e32 vcc, v4, v3
	s_nop 1
	v_cndmask_b32_e32 v4, v2, v4, vcc
	v_lshlrev_b32_e32 v23, 2, v4
	v_xor_b32_e32 v4, 16, v2
	v_cmp_lt_i32_e32 vcc, v4, v3
	s_nop 1
	v_cndmask_b32_e32 v4, v2, v4, vcc
	v_lshlrev_b32_e32 v24, 2, v4
	v_xor_b32_e32 v4, 32, v2
	v_cmp_lt_i32_e32 vcc, v4, v3
	s_nop 1
	v_cndmask_b32_e32 v2, v2, v4, vcc
	v_lshlrev_b32_e32 v25, 2, v2
	v_lshlrev_b64 v[2:3], 4, v[194:195]
	v_lshl_add_u64 v[6:7], s[54:55], 0, v[2:3]
	v_lshl_add_u64 v[10:11], v[6:7], 0, s[4:5]
	s_mov_b64 s[4:5], 0x1800
	v_lshl_add_u64 v[12:13], v[6:7], 0, s[4:5]
	s_mov_b64 s[4:5], 0x1c00
	v_lshl_add_u64 v[14:15], v[6:7], 0, s[4:5]
	s_lshl_b64 s[4:5], s[78:79], 13
	s_add_u32 s4, s52, s4
	s_addc_u32 s5, s53, s5
	v_lshl_add_u64 v[2:3], s[4:5], 0, v[2:3]
	s_ashr_i32 s89, s88, 31
	v_lshl_add_u64 v[8:9], v[6:7], 0, s[2:3]
	v_lshl_add_u64 v[16:17], v[2:3], 0, s[2:3]
	s_lshl_b64 s[4:5], s[88:89], 13
	s_lshl_b64 s[2:3], s[78:79], 12
	s_add_u32 s2, s74, s2
	s_addc_u32 s3, s75, s3
	v_lshl_add_u64 v[2:3], v[194:195], 3, s[2:3]
	s_mov_b64 s[2:3], 0x8100000
	s_mov_b32 s79, s28
	v_lshl_add_u64 v[18:19], v[2:3], 0, s[2:3]
	s_lshl_b64 s[6:7], s[88:89], 12
	s_mov_b32 s2, 0x800000
	s_mov_b32 s3, s78
	global_load_dwordx4 v[92:95], v[6:7], off
	global_load_dwordx4 v[96:99], v[6:7], off offset:1024
	global_load_dwordx4 v[100:103], v[6:7], off offset:2048
	global_load_dwordx4 v[104:107], v[6:7], off offset:3072
	global_load_dwordx4 v[108:111], v[8:9], off
	global_load_dwordx4 v[118:121], v[10:11], off
	global_load_dwordx4 v[122:125], v[12:13], off
	global_load_dwordx4 v[126:129], v[14:15], off
.LBB0_117:
	global_load_dwordx4 v[28:31], v[16:17], off offset:-4096
	global_load_dwordx4 v[32:35], v[16:17], off offset:-3072
	global_load_dwordx4 v[36:39], v[16:17], off offset:-2048
	global_load_dwordx4 v[40:43], v[16:17], off
	global_load_dwordx4 v[44:47], v[16:17], off offset:-1024
	global_load_dwordx4 v[48:51], v[16:17], off offset:1024
	global_load_dwordx4 v[2:5], v[16:17], off offset:3072
	global_load_dwordx4 v[52:55], v[16:17], off offset:2048
	s_add_i32 s3, s3, s88
	v_lshl_add_u64 v[16:17], v[16:17], 0, s[4:5]
	s_cmpk_gt_i32 s3, 0x7fff
	s_waitcnt vmcnt(7)
	v_mov_b32_e32 v62, v29
	s_waitcnt vmcnt(6)
	v_mov_b32_e32 v63, v33
	v_mov_b32_e32 v66, v31
	v_mov_b32_e32 v67, v35
	v_mov_b32_e32 v60, v28
	v_mov_b32_e32 v61, v32
	v_mov_b32_e32 v64, v30
	v_mov_b32_e32 v65, v34
	s_waitcnt vmcnt(5)
	v_pk_mul_f32 v[68:69], v[38:39], v[38:39]
	v_pk_mul_f32 v[70:71], v[36:37], v[36:37]
	v_pk_mul_f32 v[62:63], v[62:63], v[62:63]
	v_pk_mul_f32 v[66:67], v[66:67], v[66:67]
	v_pk_mov_b32 v[84:85], v[70:71], v[68:69] op_sel:[1,0]
	v_mov_b32_e32 v71, v69
	v_pk_fma_f32 v[60:61], v[60:61], v[60:61], v[62:63]
	v_pk_fma_f32 v[62:63], v[64:65], v[64:65], v[66:67]
	s_waitcnt vmcnt(3)
	v_mul_f32_e32 v72, v45, v45
	v_mul_f32_e32 v74, v47, v47
	v_pk_add_f32 v[64:65], v[84:85], v[70:71]
	v_pk_add_f32 v[60:61], v[60:61], v[62:63]
	v_mul_f32_e32 v27, v40, v40
	v_mul_f32_e32 v83, v41, v41
	v_mul_f32_e32 v86, v42, v42
	v_mul_f32_e32 v87, v43, v43
	v_pk_fma_f32 v[68:69], v[44:45], v[44:45], v[72:73] op_sel_hi:[1,1,0]
	v_pk_fma_f32 v[72:73], v[46:47], v[46:47], v[74:75] op_sel_hi:[1,1,0]
	v_pk_add_f32 v[62:63], v[64:65], v[64:65] op_sel:[0,1] op_sel_hi:[1,0]
	v_pk_add_f32 v[60:61], v[60:61], v[60:61] op_sel:[0,1] op_sel_hi:[1,0]
	s_waitcnt vmcnt(2)
	v_pk_mul_f32 v[76:77], v[50:51], v[50:51]
	v_pk_mul_f32 v[78:79], v[48:49], v[48:49]
	v_mov_b32_e32 v69, v86
	v_mov_b32_e32 v73, v87
	v_mov_b32_e32 v63, v83
	v_mov_b32_e32 v61, v27
	v_pk_mov_b32 v[74:75], v[78:79], v[76:77] op_sel:[1,0]
	v_mov_b32_e32 v79, v77
	v_pk_add_f32 v[64:65], v[68:69], v[72:73]
	v_pk_add_f32 v[60:61], v[60:61], v[62:63]
	s_waitcnt vmcnt(0)
	v_mul_f32_e32 v80, v53, v53
	v_mul_f32_e32 v82, v55, v55
	v_pk_add_f32 v[66:67], v[74:75], v[78:79]
	v_pk_add_f32 v[60:61], v[60:61], v[64:65]
	v_mul_f32_e32 v88, v2, v2
	v_mul_f32_e32 v89, v3, v3
	v_mul_f32_e32 v90, v4, v4
	v_mul_f32_e32 v91, v5, v5
	v_pk_fma_f32 v[76:77], v[52:53], v[52:53], v[80:81] op_sel_hi:[1,1,0]
	v_pk_fma_f32 v[80:81], v[54:55], v[54:55], v[82:83] op_sel_hi:[1,1,0]
	v_pk_add_f32 v[66:67], v[66:67], v[66:67] op_sel:[0,1] op_sel_hi:[1,0]
	v_pk_add_f32 v[60:61], v[60:61], v[60:61] op_sel:[0,1] op_sel_hi:[1,0]
	v_mov_b32_e32 v77, v90
	v_mov_b32_e32 v81, v91
	v_mov_b32_e32 v67, v89
	v_mov_b32_e32 v61, v88
	v_pk_add_f32 v[68:69], v[76:77], v[80:81]
	v_pk_add_f32 v[60:61], v[60:61], v[66:67]
	s_nop 0
	v_pk_add_f32 v[60:61], v[60:61], v[68:69]
	s_nop 0
	v_add_f32_e32 v27, v60, v61
	ds_bpermute_b32 v60, v20, v27
	s_waitcnt lgkmcnt(0)
	v_add_f32_e32 v27, v27, v60
	ds_bpermute_b32 v60, v21, v27
	s_waitcnt lgkmcnt(0)
	v_add_f32_e32 v27, v27, v60
	ds_bpermute_b32 v60, v22, v27
	s_waitcnt lgkmcnt(0)
	v_add_f32_e32 v27, v27, v60
	ds_bpermute_b32 v60, v23, v27
	s_waitcnt lgkmcnt(0)
	v_add_f32_e32 v27, v27, v60
	ds_bpermute_b32 v60, v24, v27
	s_waitcnt lgkmcnt(0)
	v_add_f32_e32 v27, v27, v60
	ds_bpermute_b32 v60, v25, v27
	s_waitcnt lgkmcnt(0)
	v_add_f32_e32 v27, v27, v60
	v_fmamk_f32 v27, v27, 0x3a000000, v26
	v_mul_f32_e32 v60, 0x4b800000, v27
	v_cmp_gt_f32_e32 vcc, s2, v27
	s_nop 1
	v_cndmask_b32_e32 v27, v27, v60, vcc
	v_rsq_f32_e32 v27, v27
	s_nop 0
	v_mul_f32_e32 v60, 0x45800000, v27
	v_cndmask_b32_e32 v27, v27, v60, vcc
	v_mul_f32_e32 v160, v28, v27
	v_mul_f32_e32 v161, v29, v27
	v_mul_f32_e32 v162, v30, v27
	v_mul_f32_e32 v163, v31, v27
	v_mul_f32_e32 v160, v92, v160
	v_mul_f32_e32 v161, v93, v161
	v_mul_f32_e32 v162, v94, v162
	v_mul_f32_e32 v163, v95, v163
	v_cvt_pk_bf16_f32 v164, v160, v161
	v_cvt_pk_bf16_f32 v165, v162, v163
	global_store_dwordx2 v[18:19], v[164:165], off
	v_mul_f32_e32 v168, v32, v27
	v_mul_f32_e32 v169, v33, v27
	v_mul_f32_e32 v170, v34, v27
	v_mul_f32_e32 v171, v35, v27
	v_mul_f32_e32 v168, v96, v168
	v_mul_f32_e32 v169, v97, v169
	v_mul_f32_e32 v170, v98, v170
	v_mul_f32_e32 v171, v99, v171
	v_cvt_pk_bf16_f32 v172, v168, v169
	v_cvt_pk_bf16_f32 v173, v170, v171
	global_store_dwordx2 v[18:19], v[172:173], off offset:512
	v_mul_f32_e32 v160, v36, v27
	v_mul_f32_e32 v161, v37, v27
	v_mul_f32_e32 v162, v38, v27
	v_mul_f32_e32 v163, v39, v27
	v_mul_f32_e32 v160, v100, v160
	v_mul_f32_e32 v161, v101, v161
	v_mul_f32_e32 v162, v102, v162
	v_mul_f32_e32 v163, v103, v163
	v_cvt_pk_bf16_f32 v164, v160, v161
	v_cvt_pk_bf16_f32 v165, v162, v163
	global_store_dwordx2 v[18:19], v[164:165], off offset:1024
	v_mul_f32_e32 v168, v44, v27
	v_mul_f32_e32 v169, v45, v27
	v_mul_f32_e32 v170, v46, v27
	v_mul_f32_e32 v171, v47, v27
	v_mul_f32_e32 v168, v104, v168
	v_mul_f32_e32 v169, v105, v169
	v_mul_f32_e32 v170, v106, v170
	v_mul_f32_e32 v171, v107, v171
	v_cvt_pk_bf16_f32 v172, v168, v169
	v_cvt_pk_bf16_f32 v173, v170, v171
	global_store_dwordx2 v[18:19], v[172:173], off offset:1536
	v_mul_f32_e32 v160, v40, v27
	v_mul_f32_e32 v161, v41, v27
	v_mul_f32_e32 v162, v42, v27
	v_mul_f32_e32 v163, v43, v27
	v_mul_f32_e32 v160, v108, v160
	v_mul_f32_e32 v161, v109, v161
	v_mul_f32_e32 v162, v110, v162
	v_mul_f32_e32 v163, v111, v163
	v_cvt_pk_bf16_f32 v164, v160, v161
	v_cvt_pk_bf16_f32 v165, v162, v163
	global_store_dwordx2 v[18:19], v[164:165], off offset:2048
	v_mul_f32_e32 v168, v48, v27
	v_mul_f32_e32 v169, v49, v27
	v_mul_f32_e32 v170, v50, v27
	v_mul_f32_e32 v171, v51, v27
	v_mul_f32_e32 v168, v118, v168
	v_mul_f32_e32 v169, v119, v169
	v_mul_f32_e32 v170, v120, v170
	v_mul_f32_e32 v171, v121, v171
	v_cvt_pk_bf16_f32 v172, v168, v169
	v_cvt_pk_bf16_f32 v173, v170, v171
	global_store_dwordx2 v[18:19], v[172:173], off offset:2560
	v_mul_f32_e32 v160, v52, v27
	v_mul_f32_e32 v161, v53, v27
	v_mul_f32_e32 v162, v54, v27
	v_mul_f32_e32 v163, v55, v27
	v_mul_f32_e32 v160, v122, v160
	v_mul_f32_e32 v161, v123, v161
	v_mul_f32_e32 v162, v124, v162
	v_mul_f32_e32 v163, v125, v163
	v_cvt_pk_bf16_f32 v164, v160, v161
	v_cvt_pk_bf16_f32 v165, v162, v163
	global_store_dwordx2 v[18:19], v[164:165], off offset:3072
	v_mul_f32_e32 v168, v2, v27
	v_mul_f32_e32 v169, v3, v27
	v_mul_f32_e32 v170, v4, v27
	v_mul_f32_e32 v171, v5, v27
	v_mul_f32_e32 v168, v126, v168
	v_mul_f32_e32 v169, v127, v169
	v_mul_f32_e32 v170, v128, v170
	v_mul_f32_e32 v171, v129, v171
	v_cvt_pk_bf16_f32 v172, v168, v169
	v_cvt_pk_bf16_f32 v173, v170, v171
	global_store_dwordx2 v[18:19], v[172:173], off offset:3584
	v_lshl_add_u64 v[18:19], v[18:19], 0, s[6:7]
	s_cbranch_scc0 .LBB0_117

.LBB0_905:
	s_lshl_b32 s1, s0, 8
	v_add_u32_e32 v160, s1, v162
	v_lshl_add_u32 v144, s14, 8, v164
	v_ashrrev_i32_e32 v161, 31, v160
	v_ashrrev_i32_e32 v145, 31, v144
	v_readlane_b32 s36, v235, 13
	v_readlane_b32 s37, v235, 14
	s_nop 2
	v_lshl_add_u64 v[222:223], v[144:145], 2, s[36:37]
	global_load_dwordx4 v[206:209], v[222:223], off
	global_load_dwordx4 v[210:213], v[222:223], off offset:64
	global_load_dwordx4 v[214:217], v[222:223], off offset:512
	global_load_dwordx4 v[218:221], v[222:223], off offset:576
	v_lshlrev_b64 v[128:129], 11, v[160:161]
	v_readlane_b32 s56, v235, 28
	v_lshl_add_u64 v[128:129], v[128:129], 0, v[144:145]
	v_readlane_b32 s57, v235, 29
	v_lshlrev_b64 v[146:147], 2, v[128:129]
	s_mov_b64 s[16:17], s[56:57]
	v_lshl_add_u64 v[148:149], s[16:17], 0, v[146:147]
	global_load_dwordx4 v[128:131], v[148:149], off
	v_lshl_add_u64 v[146:147], s[72:73], 0, v[146:147]
	v_or_b32_e32 v158, 16, v160
	v_ashrrev_i32_e32 v159, 31, v158
	v_or_b32_e32 v156, 32, v160
	v_ashrrev_i32_e32 v157, 31, v156
	v_or_b32_e32 v154, 48, v160
	v_ashrrev_i32_e32 v155, 31, v154
	v_add_u32_e32 v152, 0x80, v160
	v_ashrrev_i32_e32 v153, 31, v152
	v_readlane_b32 s58, v235, 30
	v_readlane_b32 s59, v235, 31
	v_readlane_b32 s60, v235, 32
	v_readlane_b32 s61, v235, 33
	v_readlane_b32 s62, v235, 34
	v_readlane_b32 s63, v235, 35
	v_readlane_b32 s64, v235, 36
	v_readlane_b32 s65, v235, 37
	v_readlane_b32 s66, v235, 38
	v_readlane_b32 s67, v235, 39
	v_readlane_b32 s68, v235, 40
	v_readlane_b32 s69, v235, 41
	v_readlane_b32 s70, v235, 42
	v_readlane_b32 s71, v235, 43
	s_waitcnt vmcnt(0)
	v_pk_add_f32 v[130:131], v[126:127], v[130:131]
	v_pk_add_f32 v[128:129], v[124:125], v[128:129]
	global_store_dwordx4 v[146:147], v[128:131], off
	global_load_dwordx4 v[124:127], v[148:149], off offset:64
	s_waitcnt vmcnt(0)
	v_pk_add_f32 v[122:123], v[122:123], v[126:127]
	v_pk_add_f32 v[120:121], v[120:121], v[124:125]
	global_store_dwordx4 v[146:147], v[120:123], off offset:64
	global_load_dwordx4 v[124:127], v[148:149], off offset:512
	s_waitcnt vmcnt(0)
	v_pk_add_f32 v[118:119], v[118:119], v[126:127]
	v_pk_add_f32 v[116:117], v[116:117], v[124:125]
	global_store_dwordx4 v[146:147], v[116:119], off offset:512
	global_load_dwordx4 v[124:127], v[148:149], off offset:576
	v_lshlrev_b64 v[148:149], 11, v[158:159]
	v_lshl_add_u64 v[148:149], v[148:149], 0, v[144:145]
	v_lshlrev_b64 v[148:149], 2, v[148:149]
	v_lshl_add_u64 v[150:151], s[16:17], 0, v[148:149]
	s_waitcnt vmcnt(0)
	v_pk_add_f32 v[126:127], v[106:107], v[126:127]
	v_pk_add_f32 v[124:125], v[104:105], v[124:125]
	global_store_dwordx4 v[146:147], v[124:127], off offset:576
	global_load_dwordx4 v[104:107], v[150:151], off
	v_lshl_add_u64 v[146:147], s[72:73], 0, v[148:149]
	v_lshlrev_b64 v[148:149], 11, v[156:157]
	v_lshl_add_u64 v[148:149], v[148:149], 0, v[144:145]
	v_lshlrev_b64 v[148:149], 2, v[148:149]
	s_waitcnt vmcnt(0)
	v_pk_add_f32 v[114:115], v[114:115], v[106:107]
	v_pk_add_f32 v[112:113], v[112:113], v[104:105]
	global_store_dwordx4 v[146:147], v[112:115], off
	global_load_dwordx4 v[104:107], v[150:151], off offset:64
	s_waitcnt vmcnt(0)
	v_pk_add_f32 v[106:107], v[110:111], v[106:107]
	v_pk_add_f32 v[104:105], v[108:109], v[104:105]
	global_store_dwordx4 v[146:147], v[104:107], off offset:64
	global_load_dwordx4 v[108:111], v[150:151], off offset:512
	s_waitcnt vmcnt(0)
	v_pk_add_f32 v[102:103], v[102:103], v[110:111]
	v_pk_add_f32 v[100:101], v[100:101], v[108:109]
	global_store_dwordx4 v[146:147], v[100:103], off offset:512
	global_load_dwordx4 v[108:111], v[150:151], off offset:576
	v_lshl_add_u64 v[150:151], s[16:17], 0, v[148:149]
	s_waitcnt vmcnt(0)
	v_pk_add_f32 v[110:111], v[90:91], v[110:111]
	v_pk_add_f32 v[108:109], v[88:89], v[108:109]
	global_store_dwordx4 v[146:147], v[108:111], off offset:576
	global_load_dwordx4 v[88:91], v[150:151], off
	v_lshl_add_u64 v[146:147], s[72:73], 0, v[148:149]
	v_lshlrev_b64 v[148:149], 11, v[154:155]
	v_lshl_add_u64 v[148:149], v[148:149], 0, v[144:145]
	v_lshlrev_b64 v[148:149], 2, v[148:149]
	s_waitcnt vmcnt(0)
	v_pk_add_f32 v[98:99], v[98:99], v[90:91]
	v_pk_add_f32 v[96:97], v[96:97], v[88:89]
	global_store_dwordx4 v[146:147], v[96:99], off
	global_load_dwordx4 v[88:91], v[150:151], off offset:64
	s_waitcnt vmcnt(0)
	v_pk_add_f32 v[90:91], v[94:95], v[90:91]
	v_pk_add_f32 v[88:89], v[92:93], v[88:89]
	global_store_dwordx4 v[146:147], v[88:91], off offset:64
	global_load_dwordx4 v[92:95], v[150:151], off offset:512
	s_waitcnt vmcnt(0)
	v_pk_add_f32 v[86:87], v[86:87], v[94:95]
	v_pk_add_f32 v[84:85], v[84:85], v[92:93]
	global_store_dwordx4 v[146:147], v[84:87], off offset:512
	global_load_dwordx4 v[92:95], v[150:151], off offset:576
	v_lshl_add_u64 v[150:151], s[16:17], 0, v[148:149]
	s_waitcnt vmcnt(0)
	v_pk_add_f32 v[94:95], v[74:75], v[94:95]
	v_pk_add_f32 v[92:93], v[72:73], v[92:93]
	global_store_dwordx4 v[146:147], v[92:95], off offset:576
	global_load_dwordx4 v[72:75], v[150:151], off
	v_lshl_add_u64 v[146:147], s[72:73], 0, v[148:149]
	v_lshlrev_b64 v[148:149], 11, v[152:153]
	v_lshl_add_u64 v[148:149], v[148:149], 0, v[144:145]
	v_lshlrev_b64 v[148:149], 2, v[148:149]
	s_waitcnt vmcnt(0)
	v_pk_add_f32 v[82:83], v[82:83], v[74:75]
	v_pk_add_f32 v[80:81], v[80:81], v[72:73]
	global_store_dwordx4 v[146:147], v[80:83], off
	global_load_dwordx4 v[72:75], v[150:151], off offset:64
	s_waitcnt vmcnt(0)
	v_pk_add_f32 v[74:75], v[78:79], v[74:75]
	v_pk_add_f32 v[72:73], v[76:77], v[72:73]
	global_store_dwordx4 v[146:147], v[72:75], off offset:64
	global_load_dwordx4 v[76:79], v[150:151], off offset:512
	s_waitcnt vmcnt(0)
	v_pk_add_f32 v[70:71], v[70:71], v[78:79]
	v_pk_add_f32 v[68:69], v[68:69], v[76:77]
	global_store_dwordx4 v[146:147], v[68:71], off offset:512
	global_load_dwordx4 v[76:79], v[150:151], off offset:576
	v_lshl_add_u64 v[150:151], s[16:17], 0, v[148:149]
	s_waitcnt vmcnt(0)
	v_pk_add_f32 v[78:79], v[66:67], v[78:79]
	v_pk_add_f32 v[76:77], v[64:65], v[76:77]
	global_store_dwordx4 v[146:147], v[76:79], off offset:576
	global_load_dwordx4 v[64:67], v[150:151], off
	v_lshl_add_u64 v[146:147], s[72:73], 0, v[148:149]
	s_waitcnt vmcnt(0)
	v_pk_add_f32 v[66:67], v[62:63], v[66:67]
	v_pk_add_f32 v[64:65], v[60:61], v[64:65]
	global_store_dwordx4 v[146:147], v[64:67], off
	global_load_dwordx4 v[60:63], v[150:151], off offset:64
	s_waitcnt vmcnt(0)
	v_pk_add_f32 v[58:59], v[58:59], v[62:63]
	v_pk_add_f32 v[56:57], v[56:57], v[60:61]
	global_store_dwordx4 v[146:147], v[56:59], off offset:64
	global_load_dwordx4 v[60:63], v[150:151], off offset:512
	s_waitcnt vmcnt(0)
	v_pk_add_f32 v[54:55], v[54:55], v[62:63]
	v_pk_add_f32 v[52:53], v[52:53], v[60:61]
	global_store_dwordx4 v[146:147], v[52:55], off offset:512
	global_load_dwordx4 v[60:63], v[150:151], off offset:576
	v_add_u32_e32 v150, 0x90, v160
	v_ashrrev_i32_e32 v151, 31, v150
	v_lshlrev_b64 v[148:149], 11, v[150:151]
	v_lshl_add_u64 v[148:149], v[148:149], 0, v[144:145]
	v_lshlrev_b64 v[148:149], 2, v[148:149]
	v_lshl_add_u64 v[174:175], s[16:17], 0, v[148:149]
	s_waitcnt vmcnt(0)
	v_pk_add_f32 v[62:63], v[42:43], v[62:63]
	v_pk_add_f32 v[60:61], v[40:41], v[60:61]
	global_store_dwordx4 v[146:147], v[60:63], off offset:576
	global_load_dwordx4 v[40:43], v[174:175], off
	v_lshl_add_u64 v[146:147], s[72:73], 0, v[148:149]
	v_add_u32_e32 v148, 0xa0, v160
	v_ashrrev_i32_e32 v149, 31, v148
	s_waitcnt vmcnt(0)
	v_pk_add_f32 v[50:51], v[50:51], v[42:43]
	v_pk_add_f32 v[48:49], v[48:49], v[40:41]
	global_store_dwordx4 v[146:147], v[48:51], off
	global_load_dwordx4 v[40:43], v[174:175], off offset:64
	s_waitcnt vmcnt(0)
	v_pk_add_f32 v[42:43], v[46:47], v[42:43]
	v_pk_add_f32 v[40:41], v[44:45], v[40:41]
	global_store_dwordx4 v[146:147], v[40:43], off offset:64
	global_load_dwordx4 v[44:47], v[174:175], off offset:512
	s_waitcnt vmcnt(0)
	v_pk_add_f32 v[38:39], v[38:39], v[46:47]
	v_pk_add_f32 v[36:37], v[36:37], v[44:45]
	global_store_dwordx4 v[146:147], v[36:39], off offset:512
	global_load_dwordx4 v[44:47], v[174:175], off offset:576
	v_lshlrev_b64 v[174:175], 11, v[148:149]
	v_lshl_add_u64 v[174:175], v[174:175], 0, v[144:145]
	v_lshlrev_b64 v[174:175], 2, v[174:175]
	v_lshl_add_u64 v[176:177], s[16:17], 0, v[174:175]
	v_lshl_add_u64 v[174:175], s[72:73], 0, v[174:175]
	s_waitcnt vmcnt(0)
	v_pk_add_f32 v[46:47], v[26:27], v[46:47]
	v_pk_add_f32 v[44:45], v[24:25], v[44:45]
	global_store_dwordx4 v[146:147], v[44:47], off offset:576
	global_load_dwordx4 v[24:27], v[176:177], off
	v_add_u32_e32 v146, 0xb0, v160
	v_ashrrev_i32_e32 v147, 31, v146
	s_waitcnt vmcnt(0)
	v_pk_add_f32 v[34:35], v[34:35], v[26:27]
	v_pk_add_f32 v[32:33], v[32:33], v[24:25]
	global_store_dwordx4 v[174:175], v[32:35], off
	global_load_dwordx4 v[24:27], v[176:177], off offset:64
	s_waitcnt vmcnt(0)
	v_pk_add_f32 v[26:27], v[30:31], v[26:27]
	v_pk_add_f32 v[24:25], v[28:29], v[24:25]
	global_store_dwordx4 v[174:175], v[24:27], off offset:64
	global_load_dwordx4 v[28:31], v[176:177], off offset:512
	s_waitcnt vmcnt(0)
	v_pk_add_f32 v[22:23], v[22:23], v[30:31]
	v_pk_add_f32 v[20:21], v[20:21], v[28:29]
	global_store_dwordx4 v[174:175], v[20:23], off offset:512
	global_load_dwordx4 v[28:31], v[176:177], off offset:576
	v_lshlrev_b64 v[176:177], 11, v[146:147]
	v_lshl_add_u64 v[176:177], v[176:177], 0, v[144:145]
	v_lshlrev_b64 v[176:177], 2, v[176:177]
	v_lshl_add_u64 v[178:179], s[16:17], 0, v[176:177]
	v_lshl_add_u64 v[180:181], s[72:73], 0, v[176:177]
	s_waitcnt vmcnt(0)
	v_pk_add_f32 v[30:31], v[10:11], v[30:31]
	v_pk_add_f32 v[28:29], v[8:9], v[28:29]
	global_store_dwordx4 v[174:175], v[28:31], off offset:576
	global_load_dwordx4 v[8:11], v[178:179], off
	s_waitcnt vmcnt(0)
	v_pk_add_f32 v[18:19], v[18:19], v[10:11]
	v_pk_add_f32 v[16:17], v[16:17], v[8:9]
	global_store_dwordx4 v[180:181], v[16:19], off
	global_load_dwordx4 v[8:11], v[178:179], off offset:64
	s_waitcnt vmcnt(0)
	v_pk_add_f32 v[10:11], v[14:15], v[10:11]
	v_pk_add_f32 v[8:9], v[12:13], v[8:9]
	global_store_dwordx4 v[180:181], v[8:11], off offset:64
	global_load_dwordx4 v[12:15], v[178:179], off offset:512
	s_waitcnt vmcnt(0)
	v_pk_add_f32 v[6:7], v[6:7], v[14:15]
	v_pk_add_f32 v[4:5], v[4:5], v[12:13]
	global_store_dwordx4 v[180:181], v[4:7], off offset:512
	global_load_dwordx4 v[174:177], v[178:179], off offset:576
	v_mul_f32_e32 v14, v129, v129
	v_mul_f32_e32 v15, v131, v131
	v_fmac_f32_e32 v14, v128, v128
	v_fmac_f32_e32 v15, v130, v130
	v_add_f32_e32 v14, v14, v15
	v_mul_f32_e32 v15, v121, v121
	v_mul_f32_e32 v178, v123, v123
	v_fmac_f32_e32 v15, v120, v120
	v_fmac_f32_e32 v178, v122, v122
	v_add_f32_e32 v15, v15, v178
	v_add_f32_e32 v14, v14, v15
	v_mul_f32_e32 v15, v117, v117
	v_mul_f32_e32 v178, v119, v119
	v_fmac_f32_e32 v15, v116, v116
	v_fmac_f32_e32 v178, v118, v118
	v_and_b32_e32 v13, 64, v182
	v_add_f32_e32 v15, v15, v178
	v_xor_b32_e32 v12, 16, v182
	v_add_u32_e32 v13, 64, v13
	v_add_f32_e32 v14, v14, v15
	v_mul_f32_e32 v15, v125, v125
	v_mul_f32_e32 v178, v127, v127
	v_cmp_lt_i32_e32 vcc, v12, v13
	v_fmac_f32_e32 v15, v124, v124
	v_fmac_f32_e32 v178, v126, v126
	v_cndmask_b32_e32 v12, v182, v12, vcc
	v_add_f32_e32 v15, v15, v178
	v_lshlrev_b32_e32 v12, 2, v12
	v_add_f32_e32 v14, v14, v15
	ds_bpermute_b32 v15, v12, v14
	v_xor_b32_e32 v178, 32, v182
	v_cmp_lt_i32_e32 vcc, v178, v13
	s_waitcnt lgkmcnt(0)
	v_add_f32_e32 v14, v14, v15
	v_cndmask_b32_e32 v13, v182, v178, vcc
	v_lshlrev_b32_e32 v13, 2, v13
	ds_bpermute_b32 v15, v13, v14
	s_waitcnt vmcnt(0)
	v_pk_add_f32 v[2:3], v[2:3], v[176:177]
	v_pk_add_f32 v[0:1], v[0:1], v[174:175]
	global_store_dwordx4 v[180:181], v[0:3], off offset:576
	s_and_saveexec_b64 s[2:3], s[6:7]
	s_cbranch_execz .LBB0_907
	s_waitcnt lgkmcnt(0)
	v_add_f32_e32 v14, v14, v15
	ds_write_b32 v173, v14

.LBB0_938:
	v_readlane_b32 s56, v235, 1
	v_readlane_b32 s68, v235, 13
	v_readlane_b32 s69, v235, 14
	v_readlane_b32 s0, v235, 19
	v_lshlrev_b64 v[160:161], 12, v[160:161]
	v_lshl_add_u64 v[12:13], v[144:145], 2, s[68:69]
	s_nop 1
	v_readlane_b32 s1, v235, 20
	s_waitcnt lgkmcnt(0)
	v_mul_f32_e32 v178, v128, v15
	v_mul_f32_e32 v179, v129, v15
	v_lshl_add_u64 v[128:129], s[0:1], 0, v[160:161]
	v_mul_f32_e32 v130, v130, v15
	v_mul_f32_e32 v131, v131, v15
	v_lshl_add_u64 v[160:161], v[144:145], 1, v[128:129]
	v_mul_f32_e32 v120, v120, v15
	v_mul_f32_e32 v121, v121, v15
	v_mul_f32_e32 v122, v122, v15
	v_mul_f32_e32 v123, v123, v15
	v_mul_f32_e32 v116, v116, v15
	v_mul_f32_e32 v117, v117, v15
	v_mul_f32_e32 v118, v118, v15
	v_mul_f32_e32 v119, v119, v15
	s_andn2_b64 vcc, exec, s[16:17]
	v_readlane_b32 s57, v235, 2
	v_readlane_b32 s58, v235, 3
	v_readlane_b32 s59, v235, 4
	v_readlane_b32 s60, v235, 5
	v_readlane_b32 s61, v235, 6
	v_readlane_b32 s62, v235, 7
	v_readlane_b32 s63, v235, 8
	v_readlane_b32 s64, v235, 9
	v_readlane_b32 s65, v235, 10
	v_readlane_b32 s66, v235, 11
	v_readlane_b32 s67, v235, 12
	v_readlane_b32 s70, v235, 15
	v_readlane_b32 s71, v235, 16
	s_waitcnt vmcnt(0)
	v_mul_f32_e32 v128, v178, v206
	v_mul_f32_e32 v129, v179, v207
	v_mul_f32_e32 v130, v130, v208
	v_mul_f32_e32 v131, v131, v209
	v_cvt_pk_bf16_f32 v128, v128, v129
	v_cvt_pk_bf16_f32 v129, v130, v131
	global_store_dwordx2 v[160:161], v[128:129], off
	s_nop 1
	s_waitcnt vmcnt(16)
	v_mul_f32_e32 v120, v120, v210
	v_mul_f32_e32 v121, v121, v211
	v_mul_f32_e32 v122, v122, v212
	v_mul_f32_e32 v123, v123, v213
	v_cvt_pk_bf16_f32 v120, v120, v121
	v_cvt_pk_bf16_f32 v121, v122, v123
	global_store_dwordx2 v[160:161], v[120:121], off offset:32
	s_nop 1
	s_waitcnt vmcnt(16)
	v_mul_f32_e32 v116, v116, v214
	v_mul_f32_e32 v117, v117, v215
	v_mul_f32_e32 v118, v118, v216
	v_mul_f32_e32 v119, v119, v217
	v_cvt_pk_bf16_f32 v116, v116, v117
	v_cvt_pk_bf16_f32 v117, v118, v119
	global_store_dwordx2 v[160:161], v[116:117], off offset:256
	s_nop 1
	v_mul_f32_e32 v120, v124, v15
	v_mul_f32_e32 v121, v125, v15
	v_mul_f32_e32 v122, v126, v15
	v_mul_f32_e32 v15, v127, v15
	v_cndmask_b32_e64 v123, 0, 1, s[16:17]
	v_cmp_ne_u32_e64 s[14:15], 1, v123
	s_waitcnt vmcnt(16)
	v_mul_f32_e32 v116, v120, v218
	v_mul_f32_e32 v117, v121, v219
	v_mul_f32_e32 v118, v122, v220
	v_mul_f32_e32 v15, v15, v221
	v_cvt_pk_bf16_f32 v116, v116, v117
	v_cvt_pk_bf16_f32 v117, v118, v15
	global_store_dwordx2 v[160:161], v[116:117], off offset:288
	s_cbranch_vccnz .LBB0_940
	ds_read_b32 v14, v167 offset:64
.LBB0_940:
	s_nop 1
	v_lshlrev_b64 v[120:121], 12, v[158:159]
	s_waitcnt lgkmcnt(0)
	v_mul_f32_e32 v15, v112, v14
	v_mul_f32_e32 v122, v113, v14
	v_mul_f32_e32 v114, v114, v14
	v_lshl_add_u64 v[112:113], s[0:1], 0, v[120:121]
	v_mul_f32_e32 v115, v115, v14
	v_lshl_add_u64 v[120:121], v[144:145], 1, v[112:113]
	s_and_b64 vcc, exec, s[14:15]
	s_waitcnt vmcnt(16)
	v_mul_f32_e32 v112, v122, v207
	v_mul_f32_e32 v113, v114, v208
	v_mul_f32_e32 v15, v15, v206
	v_mul_f32_e32 v114, v115, v209
	v_cvt_pk_bf16_f32 v112, v15, v112
	v_cvt_pk_bf16_f32 v113, v113, v114
	global_store_dwordx2 v[120:121], v[112:113], off
	s_nop 1
	v_mul_f32_e32 v15, v104, v14
	v_mul_f32_e32 v104, v105, v14
	v_mul_f32_e32 v105, v106, v14
	v_mul_f32_e32 v106, v107, v14
	s_waitcnt vmcnt(16)
	v_mul_f32_e32 v104, v104, v211
	v_mul_f32_e32 v105, v105, v212
	v_mul_f32_e32 v15, v15, v210
	v_mul_f32_e32 v106, v106, v213
	v_cvt_pk_bf16_f32 v104, v15, v104
	v_cvt_pk_bf16_f32 v105, v105, v106
	global_store_dwordx2 v[120:121], v[104:105], off offset:32
	s_nop 1
	v_mul_f32_e32 v15, v100, v14
	v_mul_f32_e32 v100, v101, v14
	v_mul_f32_e32 v101, v102, v14
	v_mul_f32_e32 v102, v103, v14
	s_waitcnt vmcnt(16)
	v_mul_f32_e32 v100, v100, v215
	v_mul_f32_e32 v101, v101, v216
	v_mul_f32_e32 v15, v15, v214
	v_mul_f32_e32 v102, v102, v217
	v_cvt_pk_bf16_f32 v100, v15, v100
	v_cvt_pk_bf16_f32 v101, v101, v102
	global_store_dwordx2 v[120:121], v[100:101], off offset:256
	s_nop 1
	v_mul_f32_e32 v15, v108, v14
	v_mul_f32_e32 v104, v109, v14
	v_mul_f32_e32 v105, v110, v14
	v_mul_f32_e32 v14, v111, v14
	s_waitcnt vmcnt(16)
	v_mul_f32_e32 v15, v15, v218
	v_mul_f32_e32 v100, v104, v219
	v_mul_f32_e32 v101, v105, v220
	v_mul_f32_e32 v102, v14, v221
	v_cvt_pk_bf16_f32 v14, v15, v100
	v_cvt_pk_bf16_f32 v15, v101, v102
	global_store_dwordx2 v[120:121], v[14:15], off offset:288
	v_mov_b32_e32 v14, 0x7fc00000
	v_mov_b32_e32 v15, 0x7fc00000
	s_cbranch_vccnz .LBB0_942
	ds_read_b32 v15, v167 offset:128
.LBB0_942:
	s_nop 1
	v_lshlrev_b64 v[104:105], 12, v[156:157]
	s_waitcnt lgkmcnt(0)
	v_mul_f32_e32 v106, v96, v15
	v_mul_f32_e32 v107, v97, v15
	v_lshl_add_u64 v[96:97], s[0:1], 0, v[104:105]
	v_mul_f32_e32 v98, v98, v15
	v_mul_f32_e32 v99, v99, v15
	v_lshl_add_u64 v[104:105], v[144:145], 1, v[96:97]
	v_mul_f32_e32 v88, v88, v15
	v_mul_f32_e32 v89, v89, v15
	v_mul_f32_e32 v90, v90, v15
	v_mul_f32_e32 v91, v91, v15
	v_mul_f32_e32 v84, v84, v15
	v_mul_f32_e32 v85, v85, v15
	v_mul_f32_e32 v86, v86, v15
	v_mul_f32_e32 v87, v87, v15
	s_and_b64 vcc, exec, s[14:15]
	s_waitcnt vmcnt(0)
	v_mul_f32_e32 v96, v106, v206
	v_mul_f32_e32 v97, v107, v207
	v_mul_f32_e32 v98, v98, v208
	v_mul_f32_e32 v99, v99, v209
	v_cvt_pk_bf16_f32 v96, v96, v97
	v_cvt_pk_bf16_f32 v97, v98, v99
	global_store_dwordx2 v[104:105], v[96:97], off
	s_nop 1
	s_waitcnt vmcnt(16)
	v_mul_f32_e32 v88, v88, v210
	v_mul_f32_e32 v89, v89, v211
	v_mul_f32_e32 v90, v90, v212
	v_mul_f32_e32 v91, v91, v213
	v_cvt_pk_bf16_f32 v88, v88, v89
	v_cvt_pk_bf16_f32 v89, v90, v91
	global_store_dwordx2 v[104:105], v[88:89], off offset:32
	s_nop 1
	s_waitcnt vmcnt(16)
	v_mul_f32_e32 v84, v84, v214
	v_mul_f32_e32 v85, v85, v215
	v_mul_f32_e32 v86, v86, v216
	v_mul_f32_e32 v87, v87, v217
	v_cvt_pk_bf16_f32 v84, v84, v85
	v_cvt_pk_bf16_f32 v85, v86, v87
	global_store_dwordx2 v[104:105], v[84:85], off offset:256
	s_nop 1
	v_mul_f32_e32 v88, v92, v15
	v_mul_f32_e32 v89, v93, v15
	v_mul_f32_e32 v90, v94, v15
	v_mul_f32_e32 v15, v95, v15
	s_waitcnt vmcnt(16)
	v_mul_f32_e32 v84, v88, v218
	v_mul_f32_e32 v85, v89, v219
	v_mul_f32_e32 v86, v90, v220
	v_mul_f32_e32 v15, v15, v221
	v_cvt_pk_bf16_f32 v84, v84, v85
	v_cvt_pk_bf16_f32 v85, v86, v15
	global_store_dwordx2 v[104:105], v[84:85], off offset:288
	s_cbranch_vccnz .LBB0_944
	ds_read_b32 v14, v167 offset:192
.LBB0_944:
	s_nop 1
	v_lshlrev_b64 v[88:89], 12, v[154:155]
	s_waitcnt lgkmcnt(0)
	v_mul_f32_e32 v15, v80, v14
	v_mul_f32_e32 v90, v81, v14
	v_mul_f32_e32 v82, v82, v14
	v_lshl_add_u64 v[80:81], s[0:1], 0, v[88:89]
	v_mul_f32_e32 v83, v83, v14
	v_lshl_add_u64 v[88:89], v[144:145], 1, v[80:81]
	s_and_b64 vcc, exec, s[14:15]
	s_waitcnt vmcnt(16)
	v_mul_f32_e32 v80, v90, v207
	v_mul_f32_e32 v81, v82, v208
	v_mul_f32_e32 v15, v15, v206
	v_mul_f32_e32 v82, v83, v209
	v_cvt_pk_bf16_f32 v80, v15, v80
	v_cvt_pk_bf16_f32 v81, v81, v82
	global_store_dwordx2 v[88:89], v[80:81], off
	s_nop 1
	v_mul_f32_e32 v15, v72, v14
	v_mul_f32_e32 v72, v73, v14
	v_mul_f32_e32 v73, v74, v14
	v_mul_f32_e32 v74, v75, v14
	s_waitcnt vmcnt(16)
	v_mul_f32_e32 v72, v72, v211
	v_mul_f32_e32 v73, v73, v212
	v_mul_f32_e32 v15, v15, v210
	v_mul_f32_e32 v74, v74, v213
	v_cvt_pk_bf16_f32 v72, v15, v72
	v_cvt_pk_bf16_f32 v73, v73, v74
	global_store_dwordx2 v[88:89], v[72:73], off offset:32
	s_nop 1
	v_mul_f32_e32 v15, v68, v14
	v_mul_f32_e32 v68, v69, v14
	v_mul_f32_e32 v69, v70, v14
	v_mul_f32_e32 v70, v71, v14
	s_waitcnt vmcnt(16)
	v_mul_f32_e32 v68, v68, v215
	v_mul_f32_e32 v69, v69, v216
	v_mul_f32_e32 v15, v15, v214
	v_mul_f32_e32 v70, v70, v217
	v_cvt_pk_bf16_f32 v68, v15, v68
	v_cvt_pk_bf16_f32 v69, v69, v70
	global_store_dwordx2 v[88:89], v[68:69], off offset:256
	s_nop 1
	v_mul_f32_e32 v15, v76, v14
	v_mul_f32_e32 v72, v77, v14
	v_mul_f32_e32 v73, v78, v14
	v_mul_f32_e32 v14, v79, v14
	s_waitcnt vmcnt(16)
	v_mul_f32_e32 v15, v15, v218
	v_mul_f32_e32 v68, v72, v219
	v_mul_f32_e32 v69, v73, v220
	v_mul_f32_e32 v70, v14, v221
	v_cvt_pk_bf16_f32 v14, v15, v68
	v_cvt_pk_bf16_f32 v15, v69, v70
	global_store_dwordx2 v[88:89], v[14:15], off offset:288
	v_mov_b32_e32 v14, 0x7fc00000
	v_mov_b32_e32 v15, 0x7fc00000
	s_cbranch_vccnz .LBB0_946
	ds_read_b32 v15, v167 offset:512
.LBB0_946:
	s_nop 1
	v_lshlrev_b64 v[72:73], 12, v[152:153]
	s_waitcnt lgkmcnt(0)
	v_mul_f32_e32 v74, v64, v15
	v_mul_f32_e32 v75, v65, v15
	v_lshl_add_u64 v[64:65], s[0:1], 0, v[72:73]
	v_mul_f32_e32 v66, v66, v15
	v_mul_f32_e32 v67, v67, v15
	v_lshl_add_u64 v[72:73], v[144:145], 1, v[64:65]
	v_mul_f32_e32 v56, v56, v15
	v_mul_f32_e32 v57, v57, v15
	v_mul_f32_e32 v58, v58, v15
	v_mul_f32_e32 v59, v59, v15
	v_mul_f32_e32 v52, v52, v15
	v_mul_f32_e32 v53, v53, v15
	v_mul_f32_e32 v54, v54, v15
	v_mul_f32_e32 v55, v55, v15
	s_and_b64 vcc, exec, s[14:15]
	s_waitcnt vmcnt(0)
	v_mul_f32_e32 v64, v74, v206
	v_mul_f32_e32 v65, v75, v207
	v_mul_f32_e32 v66, v66, v208
	v_mul_f32_e32 v67, v67, v209
	v_cvt_pk_bf16_f32 v64, v64, v65
	v_cvt_pk_bf16_f32 v65, v66, v67
	global_store_dwordx2 v[72:73], v[64:65], off
	s_nop 1
	s_waitcnt vmcnt(16)
	v_mul_f32_e32 v56, v56, v210
	v_mul_f32_e32 v57, v57, v211
	v_mul_f32_e32 v58, v58, v212
	v_mul_f32_e32 v59, v59, v213
	v_cvt_pk_bf16_f32 v56, v56, v57
	v_cvt_pk_bf16_f32 v57, v58, v59
	global_store_dwordx2 v[72:73], v[56:57], off offset:32
	s_nop 1
	s_waitcnt vmcnt(16)
	v_mul_f32_e32 v52, v52, v214
	v_mul_f32_e32 v53, v53, v215
	v_mul_f32_e32 v54, v54, v216
	v_mul_f32_e32 v55, v55, v217
	v_cvt_pk_bf16_f32 v52, v52, v53
	v_cvt_pk_bf16_f32 v53, v54, v55
	global_store_dwordx2 v[72:73], v[52:53], off offset:256
	s_nop 1
	v_mul_f32_e32 v56, v60, v15
	v_mul_f32_e32 v57, v61, v15
	v_mul_f32_e32 v58, v62, v15
	v_mul_f32_e32 v15, v63, v15
	s_waitcnt vmcnt(16)
	v_mul_f32_e32 v52, v56, v218
	v_mul_f32_e32 v53, v57, v219
	v_mul_f32_e32 v54, v58, v220
	v_mul_f32_e32 v15, v15, v221
	v_cvt_pk_bf16_f32 v52, v52, v53
	v_cvt_pk_bf16_f32 v53, v54, v15
	global_store_dwordx2 v[72:73], v[52:53], off offset:288
	s_cbranch_vccnz .LBB0_948
	ds_read_b32 v14, v167 offset:576
.LBB0_948:
	s_nop 1
	v_lshlrev_b64 v[56:57], 12, v[150:151]
	s_waitcnt lgkmcnt(0)
	v_mul_f32_e32 v15, v48, v14
	v_mul_f32_e32 v58, v49, v14
	v_mul_f32_e32 v50, v50, v14
	v_lshl_add_u64 v[48:49], s[0:1], 0, v[56:57]
	v_mul_f32_e32 v51, v51, v14
	v_lshl_add_u64 v[56:57], v[144:145], 1, v[48:49]
	s_and_b64 vcc, exec, s[14:15]
	s_waitcnt vmcnt(16)
	v_mul_f32_e32 v48, v58, v207
	v_mul_f32_e32 v49, v50, v208
	v_mul_f32_e32 v15, v15, v206
	v_mul_f32_e32 v50, v51, v209
	v_cvt_pk_bf16_f32 v48, v15, v48
	v_cvt_pk_bf16_f32 v49, v49, v50
	global_store_dwordx2 v[56:57], v[48:49], off
	s_nop 1
	v_mul_f32_e32 v15, v40, v14
	v_mul_f32_e32 v40, v41, v14
	v_mul_f32_e32 v41, v42, v14
	v_mul_f32_e32 v42, v43, v14
	s_waitcnt vmcnt(16)
	v_mul_f32_e32 v40, v40, v211
	v_mul_f32_e32 v41, v41, v212
	v_mul_f32_e32 v15, v15, v210
	v_mul_f32_e32 v42, v42, v213
	v_cvt_pk_bf16_f32 v40, v15, v40
	v_cvt_pk_bf16_f32 v41, v41, v42
	global_store_dwordx2 v[56:57], v[40:41], off offset:32
	s_nop 1
	v_mul_f32_e32 v15, v36, v14
	v_mul_f32_e32 v36, v37, v14
	v_mul_f32_e32 v37, v38, v14
	v_mul_f32_e32 v38, v39, v14
	s_waitcnt vmcnt(16)
	v_mul_f32_e32 v36, v36, v215
	v_mul_f32_e32 v37, v37, v216
	v_mul_f32_e32 v15, v15, v214
	v_mul_f32_e32 v38, v38, v217
	v_cvt_pk_bf16_f32 v36, v15, v36
	v_cvt_pk_bf16_f32 v37, v37, v38
	global_store_dwordx2 v[56:57], v[36:37], off offset:256
	s_nop 1
	v_mul_f32_e32 v15, v44, v14
	v_mul_f32_e32 v40, v45, v14
	v_mul_f32_e32 v41, v46, v14
	v_mul_f32_e32 v14, v47, v14
	s_waitcnt vmcnt(16)
	v_mul_f32_e32 v15, v15, v218
	v_mul_f32_e32 v36, v40, v219
	v_mul_f32_e32 v37, v41, v220
	v_mul_f32_e32 v38, v14, v221
	v_cvt_pk_bf16_f32 v14, v15, v36
	v_cvt_pk_bf16_f32 v15, v37, v38
	global_store_dwordx2 v[56:57], v[14:15], off offset:288
	v_mov_b32_e32 v14, 0x7fc00000
	v_mov_b32_e32 v15, 0x7fc00000
	s_cbranch_vccnz .LBB0_950
	ds_read_b32 v15, v167 offset:640
.LBB0_950:
	s_nop 1
	v_lshlrev_b64 v[40:41], 12, v[148:149]
	s_waitcnt lgkmcnt(0)
	v_mul_f32_e32 v42, v32, v15
	v_mul_f32_e32 v43, v33, v15
	v_lshl_add_u64 v[32:33], s[0:1], 0, v[40:41]
	v_mul_f32_e32 v34, v34, v15
	v_mul_f32_e32 v35, v35, v15
	v_lshl_add_u64 v[40:41], v[144:145], 1, v[32:33]
	v_mul_f32_e32 v24, v24, v15
	v_mul_f32_e32 v25, v25, v15
	v_mul_f32_e32 v26, v26, v15
	v_mul_f32_e32 v27, v27, v15
	v_mul_f32_e32 v20, v20, v15
	v_mul_f32_e32 v21, v21, v15
	v_mul_f32_e32 v22, v22, v15
	v_mul_f32_e32 v23, v23, v15
	s_and_b64 vcc, exec, s[14:15]
	s_waitcnt vmcnt(0)
	v_mul_f32_e32 v32, v42, v206
	v_mul_f32_e32 v33, v43, v207
	v_mul_f32_e32 v34, v34, v208
	v_mul_f32_e32 v35, v35, v209
	v_cvt_pk_bf16_f32 v32, v32, v33
	v_cvt_pk_bf16_f32 v33, v34, v35
	global_store_dwordx2 v[40:41], v[32:33], off
	s_nop 1
	s_waitcnt vmcnt(16)
	v_mul_f32_e32 v24, v24, v210
	v_mul_f32_e32 v25, v25, v211
	v_mul_f32_e32 v26, v26, v212
	v_mul_f32_e32 v27, v27, v213
	v_cvt_pk_bf16_f32 v24, v24, v25
	v_cvt_pk_bf16_f32 v25, v26, v27
	global_store_dwordx2 v[40:41], v[24:25], off offset:32
	s_nop 1
	s_waitcnt vmcnt(16)
	v_mul_f32_e32 v20, v20, v214
	v_mul_f32_e32 v21, v21, v215
	v_mul_f32_e32 v22, v22, v216
	v_mul_f32_e32 v23, v23, v217
	v_cvt_pk_bf16_f32 v20, v20, v21
	v_cvt_pk_bf16_f32 v21, v22, v23
	global_store_dwordx2 v[40:41], v[20:21], off offset:256
	s_nop 1
	v_mul_f32_e32 v24, v28, v15
	v_mul_f32_e32 v25, v29, v15
	v_mul_f32_e32 v26, v30, v15
	v_mul_f32_e32 v15, v31, v15
	s_waitcnt vmcnt(16)
	v_mul_f32_e32 v20, v24, v218
	v_mul_f32_e32 v21, v25, v219
	v_mul_f32_e32 v22, v26, v220
	v_mul_f32_e32 v15, v15, v221
	v_cvt_pk_bf16_f32 v20, v20, v21
	v_cvt_pk_bf16_f32 v21, v22, v15
	global_store_dwordx2 v[40:41], v[20:21], off offset:288
	s_cbranch_vccnz .LBB0_952
	ds_read_b32 v14, v167 offset:704
.LBB0_952:
	s_nop 1
	v_lshlrev_b64 v[24:25], 12, v[146:147]
	s_waitcnt lgkmcnt(0)
	v_mul_f32_e32 v15, v16, v14
	v_mul_f32_e32 v26, v17, v14
	v_mul_f32_e32 v18, v18, v14
	v_lshl_add_u64 v[16:17], s[0:1], 0, v[24:25]
	v_mul_f32_e32 v19, v19, v14
	v_lshl_add_u64 v[24:25], v[144:145], 1, v[16:17]
	v_mul_f32_e32 v8, v8, v14
	v_mul_f32_e32 v9, v9, v14
	v_mul_f32_e32 v10, v10, v14
	v_mul_f32_e32 v11, v11, v14
	v_mul_f32_e32 v4, v4, v14
	v_mul_f32_e32 v5, v5, v14
	v_mul_f32_e32 v6, v6, v14
	v_mul_f32_e32 v7, v7, v14
	v_mul_f32_e32 v0, v0, v14
	v_mul_f32_e32 v1, v1, v14
	v_mul_f32_e32 v2, v2, v14
	v_mul_f32_e32 v3, v3, v14
	s_andn2_b64 vcc, exec, s[12:13]
	s_mov_b64 s[0:1], -1
	s_waitcnt vmcnt(0)
	v_mul_f32_e32 v16, v26, v207
	v_mul_f32_e32 v17, v18, v208
	v_mul_f32_e32 v15, v15, v206
	v_mul_f32_e32 v18, v19, v209
	v_cvt_pk_bf16_f32 v16, v15, v16
	v_cvt_pk_bf16_f32 v17, v17, v18
	global_store_dwordx2 v[24:25], v[16:17], off
	s_nop 1
	s_waitcnt vmcnt(16)
	v_mul_f32_e32 v8, v8, v210
	v_mul_f32_e32 v9, v9, v211
	v_mul_f32_e32 v10, v10, v212
	v_mul_f32_e32 v11, v11, v213
	v_cvt_pk_bf16_f32 v8, v8, v9
	v_cvt_pk_bf16_f32 v9, v10, v11
	global_store_dwordx2 v[24:25], v[8:9], off offset:32
	s_nop 1
	s_waitcnt vmcnt(16)
	v_mul_f32_e32 v4, v4, v214
	v_mul_f32_e32 v5, v5, v215
	v_mul_f32_e32 v6, v6, v216
	v_mul_f32_e32 v7, v7, v217
	v_cvt_pk_bf16_f32 v4, v4, v5
	v_cvt_pk_bf16_f32 v5, v6, v7
	global_store_dwordx2 v[24:25], v[4:5], off offset:256
	s_nop 1
	s_waitcnt vmcnt(16)
	v_mul_f32_e32 v0, v0, v218
	v_mul_f32_e32 v1, v1, v219
	v_mul_f32_e32 v2, v2, v220
	v_mul_f32_e32 v3, v3, v221
	v_cvt_pk_bf16_f32 v0, v0, v1
	v_cvt_pk_bf16_f32 v1, v2, v3
	global_store_dwordx2 v[24:25], v[0:1], off offset:288
	s_cbranch_vccnz .LBB0_894
	s_andn2_b64 vcc, exec, s[18:19]
	s_cbranch_vccnz .LBB0_893
	s_barrier
	s_branch .LBB0_893

.LBB0_1087:
	v_lshl_add_u64 v[156:157], v[156:157], 2, s[86:87]
	global_load_dwordx4 v[206:209], v[156:157], off
	global_load_dwordx4 v[210:213], v[156:157], off offset:64
	global_load_dwordx4 v[214:217], v[156:157], off offset:512
	global_load_dwordx4 v[218:221], v[156:157], off offset:576
	s_waitcnt vmcnt(0)
	s_nop 1
	s_waitcnt lgkmcnt(0)
	v_pk_mul_f32 v[126:127], v[126:127], v[160:161] op_sel_hi:[1,0]
	v_pk_mul_f32 v[124:125], v[124:125], v[160:161] op_sel_hi:[1,0]
	v_pk_mul_f32 v[122:123], v[122:123], v[160:161] op_sel_hi:[1,0]
	v_pk_mul_f32 v[120:121], v[120:121], v[160:161] op_sel_hi:[1,0]
	v_pk_mul_f32 v[110:111], v[110:111], v[160:161] op_sel_hi:[1,0]
	v_pk_mul_f32 v[108:109], v[108:109], v[160:161] op_sel_hi:[1,0]
	v_pk_mul_f32 v[94:95], v[94:95], v[160:161] op_sel_hi:[1,0]
	v_pk_mul_f32 v[92:93], v[92:93], v[160:161] op_sel_hi:[1,0]
	s_andn2_b64 vcc, exec, s[14:15]
	s_waitcnt vmcnt(16)
	v_pk_mul_f32 v[126:127], v[208:209], v[126:127]
	v_pk_mul_f32 v[124:125], v[206:207], v[124:125]
	global_store_dwordx4 v[154:155], v[124:127], off
	s_nop 1
	s_waitcnt vmcnt(16)
	v_pk_mul_f32 v[122:123], v[122:123], v[212:213]
	v_pk_mul_f32 v[120:121], v[120:121], v[210:211]
	global_store_dwordx4 v[154:155], v[120:123], off offset:64
	s_nop 1
	s_waitcnt vmcnt(16)
	v_pk_mul_f32 v[110:111], v[110:111], v[216:217]
	v_pk_mul_f32 v[108:109], v[108:109], v[214:215]
	global_store_dwordx4 v[154:155], v[108:111], off offset:512
	s_nop 1
	v_cndmask_b32_e64 v120, 0, 1, s[14:15]
	v_cmp_ne_u32_e64 s[12:13], 1, v120
	s_waitcnt vmcnt(16)
	v_pk_mul_f32 v[94:95], v[94:95], v[220:221]
	v_pk_mul_f32 v[92:93], v[92:93], v[218:219]
	global_store_dwordx4 v[154:155], v[92:95], off offset:576
	s_cbranch_vccnz .LBB0_1089
	ds_read_b32 v158, v166 offset:64
.LBB0_1089:
	s_nop 1
	s_waitcnt lgkmcnt(0)
	v_pk_mul_f32 v[108:109], v[118:119], v[158:159] op_sel_hi:[1,0]
	v_pk_mul_f32 v[110:111], v[116:117], v[158:159] op_sel_hi:[1,0]
	v_pk_mul_f32 v[106:107], v[106:107], v[158:159] op_sel_hi:[1,0]
	v_pk_mul_f32 v[104:105], v[104:105], v[158:159] op_sel_hi:[1,0]
	v_pk_mul_f32 v[90:91], v[90:91], v[158:159] op_sel_hi:[1,0]
	v_pk_mul_f32 v[88:89], v[88:89], v[158:159] op_sel_hi:[1,0]
	v_pk_mul_f32 v[74:75], v[74:75], v[158:159] op_sel_hi:[1,0]
	v_pk_mul_f32 v[72:73], v[72:73], v[158:159] op_sel_hi:[1,0]
	s_and_b64 vcc, exec, s[12:13]
	s_waitcnt vmcnt(16)
	v_pk_mul_f32 v[94:95], v[208:209], v[108:109]
	v_pk_mul_f32 v[92:93], v[206:207], v[110:111]
	global_store_dwordx4 v[152:153], v[92:95], off
	s_nop 1
	s_waitcnt vmcnt(16)
	v_pk_mul_f32 v[94:95], v[106:107], v[212:213]
	v_pk_mul_f32 v[92:93], v[104:105], v[210:211]
	global_store_dwordx4 v[152:153], v[92:95], off offset:64
	s_nop 1
	s_waitcnt vmcnt(16)
	v_pk_mul_f32 v[90:91], v[90:91], v[216:217]
	v_pk_mul_f32 v[88:89], v[88:89], v[214:215]
	global_store_dwordx4 v[152:153], v[88:91], off offset:512
	s_nop 1
	s_waitcnt vmcnt(16)
	v_pk_mul_f32 v[74:75], v[74:75], v[220:221]
	v_pk_mul_f32 v[72:73], v[72:73], v[218:219]
	global_store_dwordx4 v[152:153], v[72:75], off offset:576
	s_nop 1
	v_mov_b32_e32 v72, 0x7fc00000
	v_mov_b32_e32 v74, 0x7fc00000
	s_cbranch_vccnz .LBB0_1091
	ds_read_b32 v74, v166 offset:128
.LBB0_1091:
	s_nop 1
	s_waitcnt lgkmcnt(0)
	v_pk_mul_f32 v[92:93], v[114:115], v[74:75] op_sel_hi:[1,0]
	v_pk_mul_f32 v[94:95], v[112:113], v[74:75] op_sel_hi:[1,0]
	v_pk_mul_f32 v[82:83], v[82:83], v[74:75] op_sel_hi:[1,0]
	v_pk_mul_f32 v[80:81], v[80:81], v[74:75] op_sel_hi:[1,0]
	v_pk_mul_f32 v[66:67], v[66:67], v[74:75] op_sel_hi:[1,0]
	v_pk_mul_f32 v[64:65], v[64:65], v[74:75] op_sel_hi:[1,0]
	s_and_b64 vcc, exec, s[12:13]
	s_waitcnt vmcnt(16)
	v_pk_mul_f32 v[90:91], v[208:209], v[92:93]
	v_pk_mul_f32 v[88:89], v[206:207], v[94:95]
	global_store_dwordx4 v[150:151], v[88:91], off
	s_nop 1
	v_pk_mul_f32 v[92:93], v[102:103], v[74:75] op_sel_hi:[1,0]
	v_pk_mul_f32 v[94:95], v[100:101], v[74:75] op_sel_hi:[1,0]
	s_waitcnt vmcnt(16)
	v_pk_mul_f32 v[90:91], v[92:93], v[212:213]
	v_pk_mul_f32 v[88:89], v[94:95], v[210:211]
	global_store_dwordx4 v[150:151], v[88:91], off offset:64
	s_nop 1
	s_waitcnt vmcnt(16)
	v_pk_mul_f32 v[82:83], v[82:83], v[216:217]
	v_pk_mul_f32 v[80:81], v[80:81], v[214:215]
	global_store_dwordx4 v[150:151], v[80:83], off offset:512
	s_nop 1
	s_waitcnt vmcnt(16)
	v_pk_mul_f32 v[66:67], v[66:67], v[220:221]
	v_pk_mul_f32 v[64:65], v[64:65], v[218:219]
	global_store_dwordx4 v[150:151], v[64:67], off offset:576
	s_cbranch_vccnz .LBB0_1093
	ds_read_b32 v72, v166 offset:192
.LBB0_1093:
	s_nop 1
	s_waitcnt lgkmcnt(0)
	v_pk_mul_f32 v[74:75], v[98:99], v[72:73] op_sel_hi:[1,0]
	v_pk_mul_f32 v[80:81], v[96:97], v[72:73] op_sel_hi:[1,0]
	v_pk_mul_f32 v[76:77], v[76:77], v[72:73] op_sel_hi:[1,0]
	v_pk_mul_f32 v[62:63], v[62:63], v[72:73] op_sel_hi:[1,0]
	v_pk_mul_f32 v[60:61], v[60:61], v[72:73] op_sel_hi:[1,0]
	v_pk_mul_f32 v[58:59], v[58:59], v[72:73] op_sel_hi:[1,0]
	v_pk_mul_f32 v[56:57], v[56:57], v[72:73] op_sel_hi:[1,0]
	s_and_b64 vcc, exec, s[12:13]
	s_waitcnt vmcnt(16)
	v_pk_mul_f32 v[66:67], v[208:209], v[74:75]
	v_pk_mul_f32 v[64:65], v[206:207], v[80:81]
	global_store_dwordx4 v[148:149], v[64:67], off
	s_nop 1
	v_pk_mul_f32 v[74:75], v[78:79], v[72:73] op_sel_hi:[1,0]
	s_waitcnt vmcnt(16)
	v_pk_mul_f32 v[64:65], v[76:77], v[210:211]
	v_pk_mul_f32 v[66:67], v[74:75], v[212:213]
	global_store_dwordx4 v[148:149], v[64:67], off offset:64
	s_nop 1
	s_waitcnt vmcnt(16)
	v_pk_mul_f32 v[62:63], v[62:63], v[216:217]
	v_pk_mul_f32 v[60:61], v[60:61], v[214:215]
	global_store_dwordx4 v[148:149], v[60:63], off offset:512
	s_nop 1
	s_waitcnt vmcnt(16)
	v_pk_mul_f32 v[58:59], v[58:59], v[220:221]
	v_pk_mul_f32 v[56:57], v[56:57], v[218:219]
	global_store_dwordx4 v[148:149], v[56:59], off offset:576
	s_nop 1
	v_mov_b32_e32 v56, 0x7fc00000
	v_mov_b32_e32 v58, 0x7fc00000
	s_cbranch_vccnz .LBB0_1095
	ds_read_b32 v58, v166 offset:512
.LBB0_1095:
	s_nop 1
	s_waitcnt lgkmcnt(0)
	v_pk_mul_f32 v[64:65], v[86:87], v[58:59] op_sel_hi:[1,0]
	v_pk_mul_f32 v[66:67], v[84:85], v[58:59] op_sel_hi:[1,0]
	v_pk_mul_f32 v[54:55], v[54:55], v[58:59] op_sel_hi:[1,0]
	v_pk_mul_f32 v[52:53], v[52:53], v[58:59] op_sel_hi:[1,0]
	v_pk_mul_f32 v[50:51], v[50:51], v[58:59] op_sel_hi:[1,0]
	v_pk_mul_f32 v[48:49], v[48:49], v[58:59] op_sel_hi:[1,0]
	s_and_b64 vcc, exec, s[12:13]
	s_waitcnt vmcnt(16)
	v_pk_mul_f32 v[62:63], v[208:209], v[64:65]
	v_pk_mul_f32 v[60:61], v[206:207], v[66:67]
	global_store_dwordx4 v[146:147], v[60:63], off
	s_nop 1
	v_pk_mul_f32 v[64:65], v[70:71], v[58:59] op_sel_hi:[1,0]
	v_pk_mul_f32 v[66:67], v[68:69], v[58:59] op_sel_hi:[1,0]
	s_waitcnt vmcnt(16)
	v_pk_mul_f32 v[62:63], v[64:65], v[212:213]
	v_pk_mul_f32 v[60:61], v[66:67], v[210:211]
	global_store_dwordx4 v[146:147], v[60:63], off offset:64
	s_nop 1
	s_waitcnt vmcnt(16)
	v_pk_mul_f32 v[54:55], v[54:55], v[216:217]
	v_pk_mul_f32 v[52:53], v[52:53], v[214:215]
	global_store_dwordx4 v[146:147], v[52:55], off offset:512
	s_nop 1
	s_waitcnt vmcnt(16)
	v_pk_mul_f32 v[50:51], v[50:51], v[220:221]
	v_pk_mul_f32 v[48:49], v[48:49], v[218:219]
	global_store_dwordx4 v[146:147], v[48:51], off offset:576
	s_cbranch_vccnz .LBB0_1097
	ds_read_b32 v56, v166 offset:576
.LBB0_1097:
	s_nop 1
	s_waitcnt lgkmcnt(0)
	v_pk_mul_f32 v[46:47], v[46:47], v[56:57] op_sel_hi:[1,0]
	v_pk_mul_f32 v[44:45], v[44:45], v[56:57] op_sel_hi:[1,0]
	v_pk_mul_f32 v[42:43], v[42:43], v[56:57] op_sel_hi:[1,0]
	v_pk_mul_f32 v[40:41], v[40:41], v[56:57] op_sel_hi:[1,0]
	v_pk_mul_f32 v[38:39], v[38:39], v[56:57] op_sel_hi:[1,0]
	v_pk_mul_f32 v[36:37], v[36:37], v[56:57] op_sel_hi:[1,0]
	v_pk_mul_f32 v[34:35], v[34:35], v[56:57] op_sel_hi:[1,0]
	v_pk_mul_f32 v[32:33], v[32:33], v[56:57] op_sel_hi:[1,0]
	s_and_b64 vcc, exec, s[12:13]
	s_waitcnt vmcnt(16)
	v_pk_mul_f32 v[46:47], v[208:209], v[46:47]
	v_pk_mul_f32 v[44:45], v[206:207], v[44:45]
	global_store_dwordx4 v[144:145], v[44:47], off
	s_nop 1
	s_waitcnt vmcnt(16)
	v_pk_mul_f32 v[42:43], v[42:43], v[212:213]
	v_pk_mul_f32 v[40:41], v[40:41], v[210:211]
	global_store_dwordx4 v[144:145], v[40:43], off offset:64
	s_nop 1
	s_waitcnt vmcnt(16)
	v_pk_mul_f32 v[38:39], v[38:39], v[216:217]
	v_pk_mul_f32 v[36:37], v[36:37], v[214:215]
	global_store_dwordx4 v[144:145], v[36:39], off offset:512
	s_nop 1
	s_waitcnt vmcnt(16)
	v_pk_mul_f32 v[34:35], v[34:35], v[220:221]
	v_pk_mul_f32 v[32:33], v[32:33], v[218:219]
	global_store_dwordx4 v[144:145], v[32:35], off offset:576
	s_nop 1
	v_mov_b32_e32 v32, 0x7fc00000
	v_mov_b32_e32 v34, 0x7fc00000
	s_cbranch_vccnz .LBB0_1099
	ds_read_b32 v34, v166 offset:640
.LBB0_1099:
	s_nop 1
	s_waitcnt lgkmcnt(0)
	v_pk_mul_f32 v[30:31], v[30:31], v[34:35] op_sel_hi:[1,0]
	v_pk_mul_f32 v[28:29], v[28:29], v[34:35] op_sel_hi:[1,0]
	v_pk_mul_f32 v[26:27], v[26:27], v[34:35] op_sel_hi:[1,0]
	v_pk_mul_f32 v[24:25], v[24:25], v[34:35] op_sel_hi:[1,0]
	v_pk_mul_f32 v[22:23], v[22:23], v[34:35] op_sel_hi:[1,0]
	v_pk_mul_f32 v[20:21], v[20:21], v[34:35] op_sel_hi:[1,0]
	v_pk_mul_f32 v[18:19], v[18:19], v[34:35] op_sel_hi:[1,0]
	v_pk_mul_f32 v[16:17], v[16:17], v[34:35] op_sel_hi:[1,0]
	s_and_b64 vcc, exec, s[12:13]
	s_waitcnt vmcnt(16)
	v_pk_mul_f32 v[30:31], v[208:209], v[30:31]
	v_pk_mul_f32 v[28:29], v[206:207], v[28:29]
	global_store_dwordx4 v[142:143], v[28:31], off
	s_nop 1
	s_waitcnt vmcnt(16)
	v_pk_mul_f32 v[26:27], v[26:27], v[212:213]
	v_pk_mul_f32 v[24:25], v[24:25], v[210:211]
	global_store_dwordx4 v[142:143], v[24:27], off offset:64
	s_nop 1
	s_waitcnt vmcnt(16)
	v_pk_mul_f32 v[22:23], v[22:23], v[216:217]
	v_pk_mul_f32 v[20:21], v[20:21], v[214:215]
	global_store_dwordx4 v[142:143], v[20:23], off offset:512
	s_nop 1
	s_waitcnt vmcnt(16)
	v_pk_mul_f32 v[18:19], v[18:19], v[220:221]
	v_pk_mul_f32 v[16:17], v[16:17], v[218:219]
	global_store_dwordx4 v[142:143], v[16:19], off offset:576
	s_cbranch_vccnz .LBB0_1101
	ds_read_b32 v32, v166 offset:704
.LBB0_1101:
	s_nop 1
	s_waitcnt lgkmcnt(0)
	v_pk_mul_f32 v[14:15], v[14:15], v[32:33] op_sel_hi:[1,0]
	v_pk_mul_f32 v[12:13], v[12:13], v[32:33] op_sel_hi:[1,0]
	v_pk_mul_f32 v[10:11], v[10:11], v[32:33] op_sel_hi:[1,0]
	v_pk_mul_f32 v[8:9], v[8:9], v[32:33] op_sel_hi:[1,0]
	v_pk_mul_f32 v[6:7], v[6:7], v[32:33] op_sel_hi:[1,0]
	v_pk_mul_f32 v[4:5], v[4:5], v[32:33] op_sel_hi:[1,0]
	v_pk_mul_f32 v[2:3], v[2:3], v[32:33] op_sel_hi:[1,0]
	v_pk_mul_f32 v[0:1], v[0:1], v[32:33] op_sel_hi:[1,0]
	s_and_b64 vcc, exec, s[10:11]
	s_mov_b64 s[0:1], -1
	s_waitcnt vmcnt(16)
	v_pk_mul_f32 v[14:15], v[208:209], v[14:15]
	v_pk_mul_f32 v[12:13], v[206:207], v[12:13]
	global_store_dwordx4 v[140:141], v[12:15], off
	s_nop 1
	s_waitcnt vmcnt(16)
	v_pk_mul_f32 v[10:11], v[10:11], v[212:213]
	v_pk_mul_f32 v[8:9], v[8:9], v[210:211]
	global_store_dwordx4 v[140:141], v[8:11], off offset:64
	s_nop 1
	s_waitcnt vmcnt(16)
	v_pk_mul_f32 v[6:7], v[6:7], v[216:217]
	v_pk_mul_f32 v[4:5], v[4:5], v[214:215]
	global_store_dwordx4 v[140:141], v[4:7], off offset:512
	s_nop 1
	s_waitcnt vmcnt(16)
	v_pk_mul_f32 v[2:3], v[2:3], v[220:221]
	v_pk_mul_f32 v[0:1], v[0:1], v[218:219]
	global_store_dwordx4 v[140:141], v[0:3], off offset:576
	s_cbranch_vccnz .LBB0_1039
	s_andn2_b64 vcc, exec, s[18:19]
	s_cbranch_vccnz .LBB0_1038
	s_barrier
	s_branch .LBB0_1038
